# MLA: counted lgkmcnt waits at each P.V MFMA (first consumer) instead of one lgkmcnt(0) before the first
# speedup vs baseline: 1.0062x; 1.0011x over previous
; __device__ __forceinline__ unsigned pk4_fp8(float a, float b, float c, float d) { int p = __builtin_amdgcn_cvt_pk_fp8_f32(a, b, 0, false); p = __builtin_amdgcn_cvt_pk_fp8_f32(c, d, p, true); return (unsigned)p; }
; #define SBAR() __builtin_amdgcn_sched_barrier(0)
; __device__ __forceinline__ void finishSM8(f32x16& p0, f32x16& p1, float alpha, float& l_reg, bf16x8& pa0, bf16x8& pa1) {
; #pragma unroll
;   for (int r = 0; r < 16; ++r) p1[r] = __builtin_amdgcn_exp2f(p1[r]);
;   float ps = 0;
; #pragma unroll
;   for (int r = 0; r < 16; ++r) ps += p0[r];
; #pragma unroll
;   for (int r = 0; r < 16; ++r) ps += p1[r];
;   { auto rr = __builtin_amdgcn_permlane32_swap(__float_as_uint(ps), __float_as_uint(ps), false, false); ps = __uint_as_float(rr[0]) + __uint_as_float(rr[1]); }
;   l_reg = l_reg * alpha + ps;
;   const u32x4 w0 = {pk4_fp8(p0[0], p0[1], p0[2], p0[3]), pk4_fp8(p0[4], p0[5], p0[6], p0[7]), pk4_fp8(p0[8], p0[9], p0[10], p0[11]), pk4_fp8(p0[12], p0[13], p0[14], p0[15])};
;   const u32x4 w1 = {pk4_fp8(p1[0], p1[1], p1[2], p1[3]), pk4_fp8(p1[4], p1[5], p1[6], p1[7]), pk4_fp8(p1[8], p1[9], p1[10], p1[11]), pk4_fp8(p1[12], p1[13], p1[14], p1[15])};
;   pa0 = __builtin_bit_cast(bf16x8, w0); pa1 = __builtin_bit_cast(bf16x8, w1);
; }
; __device__ __forceinline__ void pv8(f32x16* o, const char* Vs, bf16x8 pa0, bf16x8 pa1, int r32, int hi) {
;   const u32x4 a0 = __builtin_bit_cast(u32x4, pa0), a1 = __builtin_bit_cast(u32x4, pa1);
;   const i32x8 P = {(int)a0.x, (int)a0.y, (int)a0.z, (int)a0.w, (int)a1.x, (int)a1.y, (int)a1.z, (int)a1.w};
; #pragma unroll
;   for (int d0 = 0; d0 < 4; ++d0) { const char* b_ = Vs + (d0 * 32 + r32) * 80 + hi * 32;
;     const u32x4 lo = *reinterpret_cast<const u32x4*>(b_), h4 = *reinterpret_cast<const u32x4*>(b_ + 16);
;     const i32x8 V = {(int)lo.x, (int)lo.y, (int)lo.z, (int)lo.w, (int)h4.x, (int)h4.y, (int)h4.z, (int)h4.w};
;     o[d0] = __builtin_amdgcn_mfma_scale_f32_32x32x64_f8f6f4(P, V, o[d0], 0, 0, 0, 0x7F7F7F7F, 0, 0x7F7F7F7F); }
; template <int MODE, int SD> ...
;     ...
;     SBAR(); qkt<MODE>(pB0, pB1, K_lds + SHM_K, Kr_lds + SHM_KR, Qr_l, qr, q8, r32, hi);
;     FSM(pA0, pA1, alA); SG_QKT(); SBAR();
;     SLOAD(SO, (j + SD) * KVBLK); SBAR();
;     PVC(0); partialSM<MODE>(pB0, pB1, m_reg, mnB, alB, C, kbl + j * KVBLK, btab, nomask); asm volatile("" : "+v"(pB0), "+v"(pB1), "+v"(alB)); SG_PV(); SBAR();
.LBB0_655:
	ds_read_b128 v[82:85], v231 offset:49152
	ds_read_b128 v[86:89], v231 offset:49168
	ds_read_b128 v[122:125], v231 offset:49216
	ds_read_b128 v[126:129], v231 offset:49232
	ds_read_b128 v[162:165], v231 offset:49280
	ds_read_b128 v[166:169], v231 offset:49296
	ds_read_b128 v[146:149], v231 offset:55808
	ds_read_b128 v[150:153], v231 offset:55824
	ds_read_b128 v[154:157], v231 offset:55872
	ds_read_b128 v[158:161], v231 offset:55888
	ds_read_b128 v[170:173], v231 offset:55936
	ds_read_b128 v[174:177], v231 offset:55952
	global_load_dwordx4 v[182:185], v[208:209], off
	global_load_dwordx4 v[186:189], v[206:207], off
	s_and_saveexec_b64 s[20:21], s[12:13]
	global_load_dwordx4 v[178:181], v[204:205], off
	s_or_b64 exec, exec, s[20:21]
	v_lshl_add_u64 v[206:207], v[206:207], 0, v[212:213]
	v_lshl_add_u64 v[204:205], v[204:205], 0, v[210:211]
	s_waitcnt lgkmcnt(10)
	v_mfma_scale_f32_32x32x64_f8f6f4 v[82:97], v[82:89], v[114:121], 0, v216, v216 op_sel_hi:[0,0,0]
	v_exp_f32_e32 v240, v98
	v_exp_f32_e32 v242, v99
	v_exp_f32_e32 v239, v100
	v_exp_f32_e32 v241, v101
	v_exp_f32_e32 v245, v102
	v_exp_f32_e32 v246, v103
	v_add_f32_e32 v0, 0, v66
	v_add_f32_e32 v0, v67, v0
	s_waitcnt lgkmcnt(8)
	v_mfma_scale_f32_32x32x64_f8f6f4 v[82:97], v[122:129], v[130:137], v[82:97], v216, v216 op_sel_hi:[0,0,0]
	v_exp_f32_e32 v243, v104
	v_exp_f32_e32 v244, v105
	v_exp_f32_e32 v247, v106
	v_exp_f32_e32 v250, v107
	v_exp_f32_e32 v248, v108
	v_exp_f32_e32 v249, v109
	v_add_f32_e32 v0, v68, v0
	v_add_f32_e32 v236, v242, v240
	v_add_f32_e32 v0, v69, v0
	v_add_f32_e32 v236, v239, v236
	v_add_f32_e32 v236, v241, v236
	s_waitcnt lgkmcnt(6)
	v_mfma_scale_f32_32x32x64_f8f6f4 v[82:97], v[162:169], v[138:145], v[82:97], v216, v216 op_sel_hi:[0,0,0]
	v_exp_f32_e32 v191, v110
	v_exp_f32_e32 v217, v111
	v_exp_f32_e32 v251, v112
	v_exp_f32_e32 v252, v113
	v_add_f32_e32 v0, v70, v0
	v_add_f32_e32 v236, v245, v236
	v_add_f32_e32 v0, v71, v0
	v_add_f32_e32 v236, v246, v236
	v_add_f32_e32 v0, v72, v0
	v_add_f32_e32 v236, v243, v236
	v_add_f32_e32 v0, v73, v0
	v_add_f32_e32 v236, v244, v236
	s_waitcnt lgkmcnt(4)
	v_mfma_scale_f32_32x32x64_f8f6f4 v[98:113], v[146:153], v[114:121], 0, v216, v216 op_sel_hi:[0,0,0]
	v_add_f32_e32 v0, v74, v0
	v_add_f32_e32 v236, v247, v236
	v_add_f32_e32 v0, v75, v0
	v_add_f32_e32 v236, v250, v236
	v_add_f32_e32 v0, v76, v0
	v_add_f32_e32 v236, v248, v236
	v_add_f32_e32 v0, v77, v0
	v_add_f32_e32 v236, v249, v236
	v_add_f32_e32 v0, v78, v0
	v_add_f32_e32 v236, v191, v236
	s_waitcnt lgkmcnt(2)
	v_mfma_scale_f32_32x32x64_f8f6f4 v[98:113], v[154:161], v[130:137], v[98:113], v216, v216 op_sel_hi:[0,0,0]
	v_add_f32_e32 v0, v79, v0
	v_add_f32_e32 v236, v217, v236
	v_add_f32_e32 v0, v80, v0
	v_add_f32_e32 v236, v251, v236
	v_add_f32_e32 v0, v81, v0
	v_add_f32_e32 v236, v252, v236
	v_add_f32_e32 v235, v236, v0
	v_mov_b32_e32 v236, v235
	s_waitcnt lgkmcnt(0)
	v_mfma_scale_f32_32x32x64_f8f6f4 v[98:113], v[170:177], v[138:145], v[98:113], v216, v216 op_sel_hi:[0,0,0]
	s_nop 0
	v_permlane32_swap_b32_e32 v235, v236
	ds_read_b128 v[154:157], v230
	ds_read_b128 v[158:161], v230 offset:16
	ds_read_b128 v[146:149], v230 offset:2560
	ds_read_b128 v[150:153], v230 offset:2576
	ds_read_b128 v[122:125], v230 offset:5120
	ds_read_b128 v[126:129], v230 offset:5136
	ds_read_b128 v[166:169], v230 offset:7696
	v_cvt_pk_fp8_f32 v170, v66, v67
	v_cvt_pk_fp8_f32 v171, v70, v71
	v_cvt_pk_fp8_f32 v172, v74, v75
	v_cvt_pk_fp8_f32 v173, v78, v79
	v_cvt_pk_fp8_f32 v174, v240, v242
	v_cvt_pk_fp8_f32 v175, v245, v246
	v_cvt_pk_fp8_f32 v176, v247, v250
	v_cvt_pk_fp8_f32 v177, v191, v217
	v_cvt_pk_fp8_f32 v170, v68, v69 op_sel:[0,0,1]
	v_cvt_pk_fp8_f32 v171, v72, v73 op_sel:[0,0,1]
	v_cvt_pk_fp8_f32 v172, v76, v77 op_sel:[0,0,1]
	v_cvt_pk_fp8_f32 v173, v80, v81 op_sel:[0,0,1]
	v_cvt_pk_fp8_f32 v174, v239, v241 op_sel:[0,0,1]
	v_cvt_pk_fp8_f32 v175, v243, v244 op_sel:[0,0,1]
	v_cvt_pk_fp8_f32 v176, v248, v249 op_sel:[0,0,1]
	v_cvt_pk_fp8_f32 v177, v251, v252 op_sel:[0,0,1]
	v_max_f32_e32 v0, v83, v83
	v_max_f32_e32 v163, v98, v98
	v_max_f32_e32 v162, v82, v82
	v_max3_f32 v163, v163, v99, v100
	v_max_f32_e32 v0, v162, v0
	v_max3_f32 v163, v163, v101, v102
	v_max3_f32 v0, v0, v84, v85
	v_max3_f32 v163, v163, v103, v104
	v_max3_f32 v0, v0, v86, v87
	v_max3_f32 v163, v163, v105, v106
	v_max3_f32 v0, v0, v88, v89
	v_max3_f32 v163, v163, v107, v108
	v_max3_f32 v0, v0, v90, v91
	v_max3_f32 v163, v163, v109, v110
	v_max3_f32 v0, v0, v92, v93
	v_max3_f32 v163, v163, v111, v112
	v_max3_f32 v0, v0, v94, v95
	v_max_f32_e32 v163, v163, v113
	v_max3_f32 v0, v0, v96, v97
	v_max_f32_e32 v0, v0, v163
	v_mov_b32_e32 v162, v0
	s_nop 1
	v_permlane32_swap_b32_e32 v0, v162
	v_max_f32_e32 v162, v162, v162
	v_max_f32_e32 v0, v0, v0
	v_max_f32_e32 v0, v0, v162
	v_sub_f32_e32 v162, v0, v237
	v_mul_f32_e32 v162, 0x3dd53b94, v162
	v_cmp_ge_f32_e32 vcc, s57, v162
	s_cmp_eq_u64 vcc, exec
	v_max_f32_e32 v162, v237, v237
	s_cselect_b64 vcc, -1, 0
	v_max_f32_e32 v0, v162, v0
	v_cndmask_b32_e32 v238, v0, v237, vcc
	v_sub_f32_e32 v0, v237, v238
	v_mul_f32_e32 v0, 0x3dd53b94, v0
	v_exp_f32_e32 v0, v0
	ds_read_b128 v[162:165], v230 offset:7680
	s_waitcnt lgkmcnt(6)
	v_mul_f32_e32 v66, 0xbdd53b94, v238
	v_cmp_gt_f32_e32 vcc, 1.0, v0
	s_nop 0
	v_mfma_scale_f32_32x32x64_f8f6f4 v[50:65], v[170:177], v[154:161], v[50:65], v216, v216 op_sel_hi:[0,0,0]
	v_fmamk_f32 v82, v82, 0x3dd53b94, v66
	v_fmamk_f32 v83, v83, 0x3dd53b94, v66
	v_fmamk_f32 v84, v84, 0x3dd53b94, v66
	v_fmamk_f32 v85, v85, 0x3dd53b94, v66
	v_exp_f32_e32 v82, v82
	v_exp_f32_e32 v83, v83
	v_exp_f32_e32 v84, v84
	v_exp_f32_e32 v85, v85
	s_waitcnt lgkmcnt(4)
; #define SBAR() __builtin_amdgcn_sched_barrier(0)
; #define PVC(voff) do { if constexpr (MODE == 0) pv8(o, V_lds + (voff), pa0, pa1, r32, hi); else pv_d0(o, vb0 + (voff), pa0, pa1, pa2, pa3); } while (0)
; #define FSM(P0, P1, AL) do { if constexpr (MODE == 0) finishSM8(P0, P1, AL, l_reg, pa0, pa1); else finishSM(P0, P1, AL, l_reg, pa0, pa1, pa2, pa3); } while (0)
; #define SWAIT() do { if constexpr (SD == 1) asm volatile("s_waitcnt vmcnt(0)" ::: "memory"); else if constexpr (MODE == 0) asm volatile("s_waitcnt vmcnt(5)" ::: "memory"); else asm volatile("s_waitcnt vmcnt(4)" ::: "memory"); } while (0)
; #define SG_QKT() do { if (SGQ) { __builtin_amdgcn_sched_group_barrier(0x100, SGQ_PRE, 0); if constexpr (MODE == 0) { _Pragma("unroll") for (int _g = 0; _g < 6; ++_g) SG_ONE(2, 12, 3); } else { _Pragma("unroll") for (int _g = 0; _g < 16; ++_g) SG_ONE(1, 5, 1); } } } while (0)
; #define SG_PV() do { if (SGP) { __builtin_amdgcn_sched_group_barrier(0x100, SGP_PRE, 0); if constexpr (MODE == 0) { _Pragma("unroll") for (int _g = 0; _g < 4; ++_g) SG_ONE(2, 24, 4); } else { _Pragma("unroll") for (int _g = 0; _g < 16; ++_g) SG_ONE(2, 6, 1); } } } while (0)
; #define RESC(a) do { if (__any((a) < 1.f)) { if (hi == 0) al_l[r32] = (a); asm volatile("s_waitcnt lgkmcnt(0)" ::: "memory"); \
;     _Pragma("unroll") for (int d = 0; d < 4; ++d) _Pragma("unroll") for (int r = 0; r < 16; ++r) o[d][r] *= al_l[crow(r, hi)]; } } while (0)
; template <int MODE, int SD> ...
;     ...
;     PVC(0); partialSM<MODE>(pB0, pB1, m_reg, mnB, alB, C, kbl + j * KVBLK, btab, nomask); asm volatile("" : "+v"(pB0), "+v"(pB1), "+v"(alB)); SG_PV(); SBAR();
;     __syncthreads(); SWAIT(); SWRITE(0, SE);
;     RESC(alB); __syncthreads();
;     SBAR(); qkt<MODE>(pA0, pA1, K_lds, Kr_lds, Qr_l, qr, q8, r32, hi);
;     FSM(pB0, pB1, alB); SG_QKT(); SBAR();
;     if (SD == 1 || j + 3 < NT) SLOAD(SE, (j + 1 + SD) * KVBLK); SBAR();
;     PVC(SHM_V); partialSM<MODE>(pA0, pA1, m_reg, mnA, alA, C, kbl + (j + 1) * KVBLK, btab, nomask); asm volatile("" : "+v"(pA0), "+v"(pA1), "+v"(alA)); SG_PV(); SBAR();
;     __syncthreads(); SWAIT(); SWRITE(1, SO);
;     RESC(alA); __syncthreads();
	v_mfma_scale_f32_32x32x64_f8f6f4 v[34:49], v[170:177], v[146:153], v[34:49], v216, v216 op_sel_hi:[0,0,0]
	v_fmamk_f32 v86, v86, 0x3dd53b94, v66
	v_fmamk_f32 v87, v87, 0x3dd53b94, v66
	v_fmamk_f32 v88, v88, 0x3dd53b94, v66
	v_fmamk_f32 v89, v89, 0x3dd53b94, v66
	v_exp_f32_e32 v86, v86
	v_exp_f32_e32 v87, v87
	v_exp_f32_e32 v88, v88
	v_exp_f32_e32 v89, v89
	s_waitcnt lgkmcnt(2)
	v_mfma_scale_f32_32x32x64_f8f6f4 v[18:33], v[170:177], v[122:129], v[18:33], v216, v216 op_sel_hi:[0,0,0]
	v_fmamk_f32 v90, v90, 0x3dd53b94, v66
	v_fmamk_f32 v91, v91, 0x3dd53b94, v66
	v_fmamk_f32 v92, v92, 0x3dd53b94, v66
	v_fmamk_f32 v93, v93, 0x3dd53b94, v66
	v_exp_f32_e32 v90, v90
	v_exp_f32_e32 v91, v91
	v_exp_f32_e32 v92, v92
	v_exp_f32_e32 v93, v93
	s_waitcnt lgkmcnt(0)
	v_mfma_scale_f32_32x32x64_f8f6f4 v[2:17], v[170:177], v[162:169], v[2:17], v216, v216 op_sel_hi:[0,0,0]
	v_fmamk_f32 v94, v94, 0x3dd53b94, v66
	v_fmamk_f32 v95, v95, 0x3dd53b94, v66
	v_fmamk_f32 v96, v96, 0x3dd53b94, v66
	v_fmamk_f32 v97, v97, 0x3dd53b94, v66
	v_exp_f32_e32 v94, v94
	v_exp_f32_e32 v95, v95
	v_exp_f32_e32 v96, v96
	v_exp_f32_e32 v97, v97
	v_pk_fma_f32 v[98:99], v[98:99], s[78:79], v[66:67] op_sel_hi:[1,0,0]
	v_pk_fma_f32 v[100:101], v[100:101], s[78:79], v[66:67] op_sel_hi:[1,0,0]
	v_pk_fma_f32 v[102:103], v[102:103], s[78:79], v[66:67] op_sel_hi:[1,0,0]
	v_pk_fma_f32 v[104:105], v[104:105], s[78:79], v[66:67] op_sel_hi:[1,0,0]
	v_pk_fma_f32 v[106:107], v[106:107], s[78:79], v[66:67] op_sel_hi:[1,0,0]
	v_pk_fma_f32 v[108:109], v[108:109], s[78:79], v[66:67] op_sel_hi:[1,0,0]
	v_pk_fma_f32 v[110:111], v[110:111], s[78:79], v[66:67] op_sel_hi:[1,0,0]
	v_pk_fma_f32 v[112:113], v[112:113], s[78:79], v[66:67] op_sel_hi:[1,0,0]
	s_cbranch_vccz .LBB0_671
	s_and_saveexec_b64 s[20:21], s[8:9]
	ds_write_b32 v229, v0 offset:128
	s_or_b64 exec, exec, s[20:21]
	s_waitcnt lgkmcnt(0)
	ds_read_b128 v[66:69], v228 offset:224
	ds_read_b128 v[70:73], v228 offset:192
	ds_read_b128 v[74:77], v228 offset:160
	ds_read_b128 v[78:81], v228 offset:128
	s_waitcnt lgkmcnt(3)
	s_nop 7
	v_pk_mul_f32 v[64:65], v[64:65], v[68:69]
	s_waitcnt lgkmcnt(2)
	v_pk_mul_f32 v[60:61], v[60:61], v[72:73]
	s_waitcnt lgkmcnt(1)
	v_pk_mul_f32 v[56:57], v[56:57], v[76:77]
	s_waitcnt lgkmcnt(0)
	v_pk_mul_f32 v[52:53], v[52:53], v[80:81]
	v_pk_mul_f32 v[62:63], v[62:63], v[66:67]
	v_pk_mul_f32 v[58:59], v[58:59], v[70:71]
	v_pk_mul_f32 v[54:55], v[54:55], v[74:75]
	v_pk_mul_f32 v[50:51], v[50:51], v[78:79]
	v_pk_mul_f32 v[48:49], v[48:49], v[68:69]
	v_pk_mul_f32 v[44:45], v[44:45], v[72:73]
	v_pk_mul_f32 v[40:41], v[40:41], v[76:77]
	v_pk_mul_f32 v[36:37], v[36:37], v[80:81]
	v_pk_mul_f32 v[46:47], v[46:47], v[66:67]
	v_pk_mul_f32 v[42:43], v[42:43], v[70:71]
	v_pk_mul_f32 v[38:39], v[38:39], v[74:75]
	v_pk_mul_f32 v[34:35], v[34:35], v[78:79]
	v_pk_mul_f32 v[32:33], v[32:33], v[68:69]
	v_pk_mul_f32 v[28:29], v[28:29], v[72:73]
	v_pk_mul_f32 v[24:25], v[24:25], v[76:77]
	v_pk_mul_f32 v[20:21], v[20:21], v[80:81]
	v_pk_mul_f32 v[30:31], v[30:31], v[66:67]
	v_pk_mul_f32 v[26:27], v[26:27], v[70:71]
	v_pk_mul_f32 v[22:23], v[22:23], v[74:75]
	v_pk_mul_f32 v[18:19], v[18:19], v[78:79]
	v_pk_mul_f32 v[16:17], v[16:17], v[68:69]
	v_pk_mul_f32 v[12:13], v[12:13], v[72:73]
	v_pk_mul_f32 v[8:9], v[8:9], v[76:77]
	v_pk_mul_f32 v[4:5], v[4:5], v[80:81]
	v_pk_mul_f32 v[14:15], v[14:15], v[66:67]
	v_pk_mul_f32 v[10:11], v[10:11], v[70:71]
	v_pk_mul_f32 v[6:7], v[6:7], v[74:75]
	v_pk_mul_f32 v[2:3], v[2:3], v[78:79]
.LBB0_671:
	s_waitcnt vmcnt(0)
	s_waitcnt vmcnt(1)
	ds_write_b128 v225, v[182:185]
	s_waitcnt vmcnt(0)
	ds_write_b128 v226, v[186:189] offset:32768
	s_and_saveexec_b64 s[20:21], s[12:13]
	ds_write_b128 v234, v[178:181] offset:32768
	s_or_b64 exec, exec, s[20:21]
	s_lshl_b32 s26, s25, 6
	s_waitcnt lgkmcnt(0)
	s_barrier
	ds_read_b128 v[66:69], v231 offset:32768
	ds_read_b128 v[70:73], v231 offset:32784
	ds_read_b128 v[122:125], v231 offset:32832
	ds_read_b128 v[126:129], v231 offset:32848
	ds_read_b128 v[162:165], v231 offset:32896
	ds_read_b128 v[166:169], v231 offset:32912
	ds_read_b128 v[146:149], v231 offset:39424
	ds_read_b128 v[150:153], v231 offset:39440
	ds_read_b128 v[154:157], v231 offset:39488
	ds_read_b128 v[158:161], v231 offset:39504
	ds_read_b128 v[170:173], v231 offset:39552
	ds_read_b128 v[174:177], v231 offset:39568
	global_load_dwordx4 v[182:185], v[208:209], off offset:64
	global_load_dwordx4 v[186:189], v[206:207], off
	s_and_saveexec_b64 s[20:21], s[12:13]
	global_load_dwordx4 v[178:181], v[204:205], off
	s_or_b64 exec, exec, s[20:21]
	v_lshl_add_u64 v[206:207], v[206:207], 0, v[212:213]
	v_lshl_add_u64 v[204:205], v[204:205], 0, v[210:211]
	s_waitcnt lgkmcnt(10)
	v_mfma_scale_f32_32x32x64_f8f6f4 v[66:81], v[66:73], v[114:121], 0, v216, v216 op_sel_hi:[0,0,0]
	v_exp_f32_e32 v243, v98
	v_exp_f32_e32 v244, v99
	v_exp_f32_e32 v241, v100
	v_exp_f32_e32 v242, v101
	v_exp_f32_e32 v247, v102
	v_exp_f32_e32 v248, v103
	v_add_f32_e32 v239, 0, v82
	v_add_f32_e32 v239, v83, v239
	s_waitcnt lgkmcnt(8)
	v_mfma_scale_f32_32x32x64_f8f6f4 v[66:81], v[122:129], v[130:137], v[66:81], v216, v216 op_sel_hi:[0,0,0]
	v_exp_f32_e32 v245, v104
	v_exp_f32_e32 v246, v105
	v_exp_f32_e32 v249, v106
	v_exp_f32_e32 v252, v107
	v_exp_f32_e32 v250, v108
	v_exp_f32_e32 v251, v109
	v_add_f32_e32 v239, v84, v239
	v_add_f32_e32 v240, v244, v243
	v_add_f32_e32 v239, v85, v239
	v_add_f32_e32 v240, v241, v240
	v_add_f32_e32 v240, v242, v240
	s_waitcnt lgkmcnt(6)
; __device__ __forceinline__ unsigned pk4_fp8(float a, float b, float c, float d) { int p = __builtin_amdgcn_cvt_pk_fp8_f32(a, b, 0, false); p = __builtin_amdgcn_cvt_pk_fp8_f32(c, d, p, true); return (unsigned)p; }
; #define SBAR() __builtin_amdgcn_sched_barrier(0)
; __device__ __forceinline__ void finishSM8(f32x16& p0, f32x16& p1, float alpha, float& l_reg, bf16x8& pa0, bf16x8& pa1) {
; #pragma unroll
;   for (int r = 0; r < 16; ++r) p1[r] = __builtin_amdgcn_exp2f(p1[r]);
;   float ps = 0;
; #pragma unroll
;   for (int r = 0; r < 16; ++r) ps += p0[r];
; #pragma unroll
;   for (int r = 0; r < 16; ++r) ps += p1[r];
;   { auto rr = __builtin_amdgcn_permlane32_swap(__float_as_uint(ps), __float_as_uint(ps), false, false); ps = __uint_as_float(rr[0]) + __uint_as_float(rr[1]); }
;   l_reg = l_reg * alpha + ps;
;   const u32x4 w0 = {pk4_fp8(p0[0], p0[1], p0[2], p0[3]), pk4_fp8(p0[4], p0[5], p0[6], p0[7]), pk4_fp8(p0[8], p0[9], p0[10], p0[11]), pk4_fp8(p0[12], p0[13], p0[14], p0[15])};
;   const u32x4 w1 = {pk4_fp8(p1[0], p1[1], p1[2], p1[3]), pk4_fp8(p1[4], p1[5], p1[6], p1[7]), pk4_fp8(p1[8], p1[9], p1[10], p1[11]), pk4_fp8(p1[12], p1[13], p1[14], p1[15])};
;   pa0 = __builtin_bit_cast(bf16x8, w0); pa1 = __builtin_bit_cast(bf16x8, w1);
; }
; __device__ __forceinline__ void pv8(f32x16* o, const char* Vs, bf16x8 pa0, bf16x8 pa1, int r32, int hi) {
;   const u32x4 a0 = __builtin_bit_cast(u32x4, pa0), a1 = __builtin_bit_cast(u32x4, pa1);
;   const i32x8 P = {(int)a0.x, (int)a0.y, (int)a0.z, (int)a0.w, (int)a1.x, (int)a1.y, (int)a1.z, (int)a1.w};
; #pragma unroll
;   for (int d0 = 0; d0 < 4; ++d0) { const char* b_ = Vs + (d0 * 32 + r32) * 80 + hi * 32;
;     const u32x4 lo = *reinterpret_cast<const u32x4*>(b_), h4 = *reinterpret_cast<const u32x4*>(b_ + 16);
;     const i32x8 V = {(int)lo.x, (int)lo.y, (int)lo.z, (int)lo.w, (int)h4.x, (int)h4.y, (int)h4.z, (int)h4.w};
;     o[d0] = __builtin_amdgcn_mfma_scale_f32_32x32x64_f8f6f4(P, V, o[d0], 0, 0, 0, 0x7F7F7F7F, 0, 0x7F7F7F7F); }
; template <int MODE, int SD> ...
;     ...
;     SBAR(); qkt<MODE>(pA0, pA1, K_lds, Kr_lds, Qr_l, qr, q8, r32, hi);
;     FSM(pB0, pB1, alB); SG_QKT(); SBAR();
;     if (SD == 1 || j + 3 < NT) SLOAD(SE, (j + 1 + SD) * KVBLK); SBAR();
;     PVC(SHM_V); partialSM<MODE>(pA0, pA1, m_reg, mnA, alA, C, kbl + (j + 1) * KVBLK, btab, nomask); asm volatile("" : "+v"(pA0), "+v"(pA1), "+v"(alA)); SG_PV(); SBAR();
	v_mfma_scale_f32_32x32x64_f8f6f4 v[66:81], v[162:169], v[138:145], v[66:81], v216, v216 op_sel_hi:[0,0,0]
	v_exp_f32_e32 v254, v110
	v_exp_f32_e32 v191, v111
	v_exp_f32_e32 v253, v112
	v_exp_f32_e32 v217, v113
	v_add_f32_e32 v239, v86, v239
	v_add_f32_e32 v240, v247, v240
	v_add_f32_e32 v239, v87, v239
	v_add_f32_e32 v240, v248, v240
	v_add_f32_e32 v239, v88, v239
	v_add_f32_e32 v240, v245, v240
	v_add_f32_e32 v239, v89, v239
	v_add_f32_e32 v240, v246, v240
	s_waitcnt lgkmcnt(4)
	v_mfma_scale_f32_32x32x64_f8f6f4 v[98:113], v[146:153], v[114:121], 0, v216, v216 op_sel_hi:[0,0,0]
	v_add_f32_e32 v239, v90, v239
	v_add_f32_e32 v240, v249, v240
	v_add_f32_e32 v239, v91, v239
	v_add_f32_e32 v240, v252, v240
	v_add_f32_e32 v239, v92, v239
	v_add_f32_e32 v240, v250, v240
	v_add_f32_e32 v239, v93, v239
	v_add_f32_e32 v240, v251, v240
	v_add_f32_e32 v239, v94, v239
	v_add_f32_e32 v240, v254, v240
	s_waitcnt lgkmcnt(2)
	v_mfma_scale_f32_32x32x64_f8f6f4 v[98:113], v[154:161], v[130:137], v[98:113], v216, v216 op_sel_hi:[0,0,0]
	v_add_f32_e32 v239, v95, v239
	v_add_f32_e32 v240, v191, v240
	v_add_f32_e32 v239, v96, v239
	v_add_f32_e32 v240, v253, v240
	v_add_f32_e32 v239, v97, v239
	v_add_f32_e32 v240, v217, v240
	v_add_f32_e32 v239, v240, v239
	v_mov_b32_e32 v240, v239
	s_waitcnt lgkmcnt(0)
	v_mfma_scale_f32_32x32x64_f8f6f4 v[98:113], v[170:177], v[138:145], v[98:113], v216, v216 op_sel_hi:[0,0,0]
	s_nop 0
	v_permlane32_swap_b32_e32 v239, v240
	ds_read_b128 v[154:157], v230 offset:18432
	ds_read_b128 v[158:161], v230 offset:18448
	ds_read_b128 v[146:149], v230 offset:20992
	ds_read_b128 v[150:153], v230 offset:21008
	ds_read_b128 v[122:125], v230 offset:23552
	ds_read_b128 v[126:129], v230 offset:23568
	ds_read_b128 v[166:169], v230 offset:26128
	v_cvt_pk_fp8_f32 v82, v82, v83
	v_cvt_pk_fp8_f32 v83, v86, v87
	v_cvt_pk_fp8_f32 v82, v84, v85 op_sel:[0,0,1]
	v_cvt_pk_fp8_f32 v83, v88, v89 op_sel:[0,0,1]
	v_cvt_pk_fp8_f32 v84, v90, v91
	v_cvt_pk_fp8_f32 v85, v94, v95
	v_cvt_pk_fp8_f32 v84, v92, v93 op_sel:[0,0,1]
	v_cvt_pk_fp8_f32 v85, v96, v97 op_sel:[0,0,1]
	v_cvt_pk_fp8_f32 v86, v243, v244
	v_cvt_pk_fp8_f32 v87, v247, v248
	v_cvt_pk_fp8_f32 v86, v241, v242 op_sel:[0,0,1]
	v_cvt_pk_fp8_f32 v87, v245, v246 op_sel:[0,0,1]
	v_cvt_pk_fp8_f32 v88, v249, v252
	v_cvt_pk_fp8_f32 v89, v254, v191
	v_cvt_pk_fp8_f32 v88, v250, v251 op_sel:[0,0,1]
	v_cvt_pk_fp8_f32 v89, v253, v217 op_sel:[0,0,1]
	v_max_f32_e32 v162, v67, v67
	v_max_f32_e32 v164, v98, v98
	v_max_f32_e32 v163, v66, v66
	v_max3_f32 v164, v164, v99, v100
	v_max_f32_e32 v162, v163, v162
	v_max3_f32 v164, v164, v101, v102
	v_max3_f32 v162, v162, v68, v69
	v_max3_f32 v164, v164, v103, v104
	v_max3_f32 v162, v162, v70, v71
	v_max3_f32 v164, v164, v105, v106
	v_max3_f32 v162, v162, v72, v73
	v_max3_f32 v164, v164, v107, v108
	v_max3_f32 v162, v162, v74, v75
	v_max3_f32 v164, v164, v109, v110
	v_max3_f32 v162, v162, v76, v77
	v_max3_f32 v164, v164, v111, v112
	v_max3_f32 v162, v162, v78, v79
	v_max_f32_e32 v164, v164, v113
	v_max3_f32 v162, v162, v80, v81
	v_max_f32_e32 v162, v162, v164
	v_mov_b32_e32 v163, v162
	s_nop 1
	v_permlane32_swap_b32_e32 v162, v163
	v_max_f32_e32 v163, v163, v163
	v_max_f32_e32 v162, v162, v162
	v_max_f32_e32 v162, v162, v163
	v_sub_f32_e32 v163, v162, v238
	v_mul_f32_e32 v163, 0x3dd53b94, v163
	v_cmp_ge_f32_e32 vcc, s57, v163
	s_cmp_eq_u64 vcc, exec
	v_max_f32_e32 v163, v238, v238
	s_cselect_b64 vcc, -1, 0
	v_max_f32_e32 v162, v163, v162
	v_cndmask_b32_e32 v237, v162, v238, vcc
	v_sub_f32_e32 v170, v238, v237
	v_mul_f32_e32 v170, 0x3dd53b94, v170
	v_exp_f32_e32 v170, v170
	ds_read_b128 v[162:165], v230 offset:26112
	s_waitcnt lgkmcnt(6)
	v_mul_f32_e32 v172, 0xbdd53b94, v237
	v_cmp_gt_f32_e32 vcc, 1.0, v170
	s_nop 0
	v_mfma_scale_f32_32x32x64_f8f6f4 v[50:65], v[82:89], v[154:161], v[50:65], v216, v216 op_sel_hi:[0,0,0]
	v_fmamk_f32 v66, v66, 0x3dd53b94, v172
	v_fmamk_f32 v67, v67, 0x3dd53b94, v172
	v_fmamk_f32 v68, v68, 0x3dd53b94, v172
	v_fmamk_f32 v69, v69, 0x3dd53b94, v172
	v_exp_f32_e32 v66, v66
	v_exp_f32_e32 v67, v67
	v_exp_f32_e32 v68, v68
	v_exp_f32_e32 v69, v69
	s_waitcnt lgkmcnt(4)
	v_mfma_scale_f32_32x32x64_f8f6f4 v[34:49], v[82:89], v[146:153], v[34:49], v216, v216 op_sel_hi:[0,0,0]
	v_fmamk_f32 v70, v70, 0x3dd53b94, v172
	v_fmamk_f32 v71, v71, 0x3dd53b94, v172
	v_fmamk_f32 v72, v72, 0x3dd53b94, v172
	v_fmamk_f32 v73, v73, 0x3dd53b94, v172
	v_exp_f32_e32 v70, v70
	v_exp_f32_e32 v71, v71
	v_exp_f32_e32 v72, v72
	v_exp_f32_e32 v73, v73
	s_waitcnt lgkmcnt(2)
	v_mfma_scale_f32_32x32x64_f8f6f4 v[18:33], v[82:89], v[122:129], v[18:33], v216, v216 op_sel_hi:[0,0,0]
	v_fmamk_f32 v74, v74, 0x3dd53b94, v172
	v_fmamk_f32 v75, v75, 0x3dd53b94, v172
	v_fmamk_f32 v76, v76, 0x3dd53b94, v172
	v_fmamk_f32 v77, v77, 0x3dd53b94, v172
	v_exp_f32_e32 v74, v74
	v_exp_f32_e32 v75, v75
	v_exp_f32_e32 v76, v76
	v_exp_f32_e32 v77, v77
	s_waitcnt lgkmcnt(0)
	v_mfma_scale_f32_32x32x64_f8f6f4 v[2:17], v[82:89], v[162:169], v[2:17], v216, v216 op_sel_hi:[0,0,0]
	v_fmamk_f32 v78, v78, 0x3dd53b94, v172
	v_fmamk_f32 v79, v79, 0x3dd53b94, v172
	v_fmamk_f32 v80, v80, 0x3dd53b94, v172
	v_fmamk_f32 v81, v81, 0x3dd53b94, v172
	v_exp_f32_e32 v78, v78
	v_exp_f32_e32 v79, v79
	v_exp_f32_e32 v80, v80
	v_exp_f32_e32 v81, v81
	v_pk_fma_f32 v[98:99], v[98:99], s[78:79], v[172:173] op_sel_hi:[1,0,0]
	v_pk_fma_f32 v[100:101], v[100:101], s[78:79], v[172:173] op_sel_hi:[1,0,0]
	v_pk_fma_f32 v[102:103], v[102:103], s[78:79], v[172:173] op_sel_hi:[1,0,0]
	v_pk_fma_f32 v[104:105], v[104:105], s[78:79], v[172:173] op_sel_hi:[1,0,0]
	v_pk_fma_f32 v[106:107], v[106:107], s[78:79], v[172:173] op_sel_hi:[1,0,0]
	v_pk_fma_f32 v[108:109], v[108:109], s[78:79], v[172:173] op_sel_hi:[1,0,0]
	v_pk_fma_f32 v[110:111], v[110:111], s[78:79], v[172:173] op_sel_hi:[1,0,0]
	v_pk_fma_f32 v[112:113], v[112:113], s[78:79], v[172:173] op_sel_hi:[1,0,0]
	s_cbranch_vccz .LBB0_654
	s_and_saveexec_b64 s[20:21], s[8:9]
	s_cbranch_execz .LBB0_653
	ds_write_b32 v229, v170 offset:128
	s_branch .LBB0_653
